# attention main path: all four first-group V fragments read ahead of the QK MFMAs (two PV waits removed)
# baseline (speedup 1.0000x reference)
.LBB0_185:
	ds_read_b128 v[126:129], v244 offset:16384
	ds_read_b128 v[194:197], v244 offset:20480
	ds_read_b128 v[198:201], v244 offset:24576
	ds_read_b128 v[202:205], v244 offset:28672
	s_waitcnt lgkmcnt(4)
	v_mfma_f32_32x32x16_bf16 v[82:97], v[98:101], v[146:149], v[66:81]
	ds_read_b128 v[122:125], v240 offset:24576
	v_mfma_f32_32x32x16_bf16 v[98:113], v[114:117], v[146:149], v[66:81]
	ds_read_b128 v[114:117], v241 offset:16384
	v_mfma_f32_32x32x16_bf16 v[82:97], v[118:121], v[150:153], v[82:97]
	ds_read_b128 v[118:121], v241 offset:24576
	s_waitcnt lgkmcnt(0)
	v_mfma_f32_32x32x16_bf16 v[98:113], v[122:125], v[150:153], v[98:113]
	ds_read_b128 v[122:125], v243 offset:16384
	v_mfma_f32_32x32x16_bf16 v[82:97], v[114:117], v[154:157], v[82:97]
	ds_read_b128 v[114:117], v243 offset:24576
	v_mfma_f32_32x32x16_bf16 v[98:113], v[118:121], v[154:157], v[98:113]
	s_waitcnt lgkmcnt(0)
	v_mfma_f32_32x32x16_bf16 v[82:97], v[122:125], v[158:161], v[82:97]
	v_mfma_f32_32x32x16_bf16 v[98:113], v[114:117], v[158:161], v[98:113]
	s_nop 0
	s_add_i32 s22, s21, 64
	s_cmp_le_u32 s22, s20
	s_cbranch_scc0 .Lnear_u1e
.LBB0_188:
	v_mfma_f32_32x32x16_bf16 v[34:49], v[126:129], v[162:165], v[34:49]
	ds_read_b128 v[126:129], v245 offset:16384
	s_nop 0
	v_exp_f32_e32 v130, v82
	v_exp_f32_e32 v131, v83
	v_add_f32_e32 v132, v1, v130
	v_add_f32_e32 v133, v1, v131
	v_cvt_pk_bf16_f32 v166, v130, v131
	v_mfma_f32_32x32x16_bf16 v[50:65], v[194:197], v[162:165], v[50:65]
	ds_read_b128 v[122:125], v245 offset:20480
	v_exp_f32_e32 v134, v84
	v_exp_f32_e32 v135, v85
	s_add_i32 s22, s23, 2
	v_add_f32_e32 v130, v132, v134
	v_add_f32_e32 v131, v133, v135
	v_cvt_pk_bf16_f32 v167, v134, v135
	s_mov_b32 m0, s11
	s_cmp_ge_u32 s22, s17
	s_cbranch_scc1 .LBB0_190
	global_load_lds_dwordx4 v214, s[80:81]
	s_add_i32 m0, s11, 0x2000
	s_nop 0
	global_load_lds_dwordx4 v214, s[62:63]
.LBB0_190:
	v_mfma_f32_32x32x16_bf16 v[18:33], v[198:201], v[162:165], v[18:33]
	ds_read_b128 v[118:121], v245 offset:24576
	v_exp_f32_e32 v132, v86
	v_exp_f32_e32 v133, v87
	v_add_f32_e32 v130, v130, v132
	v_add_f32_e32 v131, v131, v133
	v_cvt_pk_bf16_f32 v168, v132, v133
	v_mfma_f32_32x32x16_bf16 v[2:17], v[202:205], v[162:165], v[2:17]
	ds_read_b128 v[114:117], v245 offset:28672
	v_exp_f32_e32 v132, v88
	v_exp_f32_e32 v133, v89
	v_add_f32_e32 v134, v130, v132
	v_add_f32_e32 v131, v131, v133
	v_cvt_pk_bf16_f32 v169, v132, v133
	s_waitcnt lgkmcnt(2)
	v_mfma_f32_32x32x16_bf16 v[34:49], v[126:129], v[170:173], v[34:49]
	ds_read_b128 v[126:129], v246 offset:16384
	v_exp_f32_e32 v132, v90
	v_exp_f32_e32 v133, v91
	v_add_f32_e32 v134, v134, v132
	v_add_f32_e32 v135, v131, v133
	v_cvt_pk_bf16_f32 v174, v132, v133
	v_mfma_f32_32x32x16_bf16 v[50:65], v[122:125], v[170:173], v[50:65]
	ds_read_b128 v[122:125], v246 offset:20480
	v_exp_f32_e32 v133, v92
	v_exp_f32_e32 v136, v93
	v_add_f32_e32 v131, v134, v133
	v_add_f32_e32 v132, v135, v136
	v_cvt_pk_bf16_f32 v175, v133, v136

.LBB0_225:
	ds_read_b128 v[126:129], v244 offset:32768
	ds_read_b128 v[194:197], v244 offset:36864
	ds_read_b128 v[198:201], v244 offset:40960
	ds_read_b128 v[202:205], v244 offset:45056
	s_waitcnt lgkmcnt(4)
	v_mfma_f32_32x32x16_bf16 v[82:97], v[98:101], v[146:149], v[66:81]
	ds_read_b128 v[122:125], v240 offset:40960
	v_mfma_f32_32x32x16_bf16 v[98:113], v[114:117], v[146:149], v[66:81]
	ds_read_b128 v[114:117], v241 offset:32768
	v_mfma_f32_32x32x16_bf16 v[82:97], v[118:121], v[150:153], v[82:97]
	ds_read_b128 v[118:121], v241 offset:40960
	s_waitcnt lgkmcnt(0)
	v_mfma_f32_32x32x16_bf16 v[98:113], v[122:125], v[150:153], v[98:113]
	ds_read_b128 v[122:125], v243 offset:32768
	v_mfma_f32_32x32x16_bf16 v[82:97], v[114:117], v[154:157], v[82:97]
	ds_read_b128 v[114:117], v243 offset:40960
	v_mfma_f32_32x32x16_bf16 v[98:113], v[118:121], v[154:157], v[98:113]
	s_waitcnt lgkmcnt(0)
	v_mfma_f32_32x32x16_bf16 v[82:97], v[122:125], v[158:161], v[82:97]
	v_mfma_f32_32x32x16_bf16 v[98:113], v[114:117], v[158:161], v[98:113]
	s_nop 0
	s_add_i32 s26, s21, 0x80
	s_cmp_le_u32 s26, s20
	s_cbranch_scc0 .Lnear_u1o
.LBB0_228:
	v_mfma_f32_32x32x16_bf16 v[34:49], v[126:129], v[166:169], v[34:49]
	ds_read_b128 v[126:129], v245 offset:32768
	s_nop 0
	v_exp_f32_e32 v130, v82
	v_exp_f32_e32 v131, v83
	v_add_f32_e32 v132, v1, v130
	v_add_f32_e32 v133, v1, v131
	v_cvt_pk_bf16_f32 v162, v130, v131
	v_mfma_f32_32x32x16_bf16 v[50:65], v[194:197], v[166:169], v[50:65]
	ds_read_b128 v[122:125], v245 offset:36864
	v_exp_f32_e32 v130, v84
	v_exp_f32_e32 v131, v85
	s_add_i32 s23, s23, 3
	v_add_f32_e32 v132, v132, v130
	v_add_f32_e32 v133, v133, v131
	v_cvt_pk_bf16_f32 v163, v130, v131
	s_add_i32 m0, s11, 0x4000
	s_cmp_gt_u32 s23, s16
	s_cbranch_scc1 .LBB0_230
	global_load_lds_dwordx4 v214, s[50:51]
	s_add_i32 m0, s11, 0x6000
	s_nop 0
	global_load_lds_dwordx4 v214, s[4:5]
.LBB0_230:
	v_mfma_f32_32x32x16_bf16 v[18:33], v[198:201], v[166:169], v[18:33]
	ds_read_b128 v[118:121], v245 offset:40960
	v_exp_f32_e32 v134, v86
	v_exp_f32_e32 v135, v87
	v_add_f32_e32 v132, v132, v134
	v_add_f32_e32 v133, v133, v135
	v_cvt_pk_bf16_f32 v164, v134, v135
	v_mfma_f32_32x32x16_bf16 v[2:17], v[202:205], v[166:169], v[2:17]
	ds_read_b128 v[114:117], v245 offset:45056
	v_exp_f32_e32 v134, v88
	v_exp_f32_e32 v135, v89
	v_add_f32_e32 v136, v132, v134
	v_add_f32_e32 v133, v133, v135
	v_cvt_pk_bf16_f32 v165, v134, v135
	s_waitcnt lgkmcnt(2)
	v_mfma_f32_32x32x16_bf16 v[34:49], v[126:129], v[174:177], v[34:49]
	ds_read_b128 v[126:129], v246 offset:32768
	v_exp_f32_e32 v134, v90
	v_exp_f32_e32 v135, v91
	v_add_f32_e32 v136, v136, v134
	v_add_f32_e32 v137, v133, v135
	v_cvt_pk_bf16_f32 v170, v134, v135
	v_mfma_f32_32x32x16_bf16 v[50:65], v[122:125], v[174:177], v[50:65]
	ds_read_b128 v[122:125], v246 offset:36864
	v_exp_f32_e32 v135, v92
	v_exp_f32_e32 v138, v93
	v_add_f32_e32 v133, v136, v135
	v_add_f32_e32 v134, v137, v138
	v_cvt_pk_bf16_f32 v171, v135, v138

.Lr1u1_LBB0_185:
	ds_read_b128 v[126:129], v244 offset:49152
	ds_read_b128 v[194:197], v244 offset:53248
	ds_read_b128 v[198:201], v244 offset:57344
	ds_read_b128 v[202:205], v244 offset:61440
	s_waitcnt lgkmcnt(4)
	v_mfma_f32_32x32x16_bf16 v[82:97], v[98:101], v[146:149], v[66:81]
	ds_read_b128 v[122:125], v240 offset:8192
	v_mfma_f32_32x32x16_bf16 v[98:113], v[114:117], v[146:149], v[66:81]
	ds_read_b128 v[114:117], v241
	v_mfma_f32_32x32x16_bf16 v[82:97], v[118:121], v[150:153], v[82:97]
	ds_read_b128 v[118:121], v241 offset:8192
	s_waitcnt lgkmcnt(0)
	v_mfma_f32_32x32x16_bf16 v[98:113], v[122:125], v[150:153], v[98:113]
	ds_read_b128 v[122:125], v243
	v_mfma_f32_32x32x16_bf16 v[82:97], v[114:117], v[154:157], v[82:97]
	ds_read_b128 v[114:117], v243 offset:8192
	v_mfma_f32_32x32x16_bf16 v[98:113], v[118:121], v[154:157], v[98:113]
	s_waitcnt lgkmcnt(0)
	v_mfma_f32_32x32x16_bf16 v[82:97], v[122:125], v[158:161], v[82:97]
	v_mfma_f32_32x32x16_bf16 v[98:113], v[114:117], v[158:161], v[98:113]
	s_nop 0
	s_add_i32 s22, s21, 64
	s_cmp_le_u32 s22, s20
	s_cbranch_scc0 .Lr1u1_Lnear_u1e
.Lr1u1_LBB0_188:
	v_mfma_f32_32x32x16_bf16 v[34:49], v[126:129], v[162:165], v[34:49]
	ds_read_b128 v[126:129], v245 offset:49152
	s_nop 0
	v_exp_f32_e32 v130, v82
	v_exp_f32_e32 v131, v83
	v_add_f32_e32 v132, v1, v130
	v_add_f32_e32 v133, v1, v131
	v_cvt_pk_bf16_f32 v166, v130, v131
	v_mfma_f32_32x32x16_bf16 v[50:65], v[194:197], v[162:165], v[50:65]
	ds_read_b128 v[122:125], v245 offset:53248
	v_exp_f32_e32 v134, v84
	v_exp_f32_e32 v135, v85
	s_add_i32 s22, s23, 2
	v_add_f32_e32 v130, v132, v134
	v_add_f32_e32 v131, v133, v135
	v_cvt_pk_bf16_f32 v167, v134, v135
	s_add_i32 m0, s11, 0x8000
	s_cmp_ge_u32 s22, s17
	s_cbranch_scc1 .Lr1u1_LBB0_190
	global_load_lds_dwordx4 v214, s[80:81]
	s_add_i32 m0, s11, 0xa000
	s_nop 0
	global_load_lds_dwordx4 v214, s[62:63]
.Lr1u1_LBB0_190:
	v_mfma_f32_32x32x16_bf16 v[18:33], v[198:201], v[162:165], v[18:33]
	ds_read_b128 v[118:121], v245 offset:57344
	v_exp_f32_e32 v132, v86
	v_exp_f32_e32 v133, v87
	v_add_f32_e32 v130, v130, v132
	v_add_f32_e32 v131, v131, v133
	v_cvt_pk_bf16_f32 v168, v132, v133
	v_mfma_f32_32x32x16_bf16 v[2:17], v[202:205], v[162:165], v[2:17]
	ds_read_b128 v[114:117], v245 offset:61440
	v_exp_f32_e32 v132, v88
	v_exp_f32_e32 v133, v89
	v_add_f32_e32 v134, v130, v132
	v_add_f32_e32 v131, v131, v133
	v_cvt_pk_bf16_f32 v169, v132, v133
	s_waitcnt lgkmcnt(2)
	v_mfma_f32_32x32x16_bf16 v[34:49], v[126:129], v[170:173], v[34:49]
	ds_read_b128 v[126:129], v246 offset:49152
	v_exp_f32_e32 v132, v90
	v_exp_f32_e32 v133, v91
	v_add_f32_e32 v134, v134, v132
	v_add_f32_e32 v135, v131, v133
	v_cvt_pk_bf16_f32 v174, v132, v133
	v_mfma_f32_32x32x16_bf16 v[50:65], v[122:125], v[170:173], v[50:65]
	ds_read_b128 v[122:125], v246 offset:53248
	v_exp_f32_e32 v133, v92
	v_exp_f32_e32 v136, v93
	v_add_f32_e32 v131, v134, v133
	v_add_f32_e32 v132, v135, v136
	v_cvt_pk_bf16_f32 v175, v133, v136

.Lr1u1_LBB0_225:
	ds_read_b128 v[126:129], v244 offset:16384
	ds_read_b128 v[194:197], v244 offset:20480
	ds_read_b128 v[198:201], v244 offset:24576
	ds_read_b128 v[202:205], v244 offset:28672
	s_waitcnt lgkmcnt(4)
	v_mfma_f32_32x32x16_bf16 v[82:97], v[98:101], v[146:149], v[66:81]
	ds_read_b128 v[122:125], v240 offset:24576
	v_mfma_f32_32x32x16_bf16 v[98:113], v[114:117], v[146:149], v[66:81]
	ds_read_b128 v[114:117], v241 offset:16384
	v_mfma_f32_32x32x16_bf16 v[82:97], v[118:121], v[150:153], v[82:97]
	ds_read_b128 v[118:121], v241 offset:24576
	s_waitcnt lgkmcnt(0)
	v_mfma_f32_32x32x16_bf16 v[98:113], v[122:125], v[150:153], v[98:113]
	ds_read_b128 v[122:125], v243 offset:16384
	v_mfma_f32_32x32x16_bf16 v[82:97], v[114:117], v[154:157], v[82:97]
	ds_read_b128 v[114:117], v243 offset:24576
	v_mfma_f32_32x32x16_bf16 v[98:113], v[118:121], v[154:157], v[98:113]
	s_waitcnt lgkmcnt(0)
	v_mfma_f32_32x32x16_bf16 v[82:97], v[122:125], v[158:161], v[82:97]
	v_mfma_f32_32x32x16_bf16 v[98:113], v[114:117], v[158:161], v[98:113]
	s_nop 0
	s_add_i32 s26, s21, 0x80
	s_cmp_le_u32 s26, s20
	s_cbranch_scc0 .Lr1u1_Lnear_u1o
.Lr1u1_LBB0_228:
	v_mfma_f32_32x32x16_bf16 v[34:49], v[126:129], v[166:169], v[34:49]
	ds_read_b128 v[126:129], v245 offset:16384
	s_nop 0
	v_exp_f32_e32 v130, v82
	v_exp_f32_e32 v131, v83
	v_add_f32_e32 v132, v1, v130
	v_add_f32_e32 v133, v1, v131
	v_cvt_pk_bf16_f32 v162, v130, v131
	v_mfma_f32_32x32x16_bf16 v[50:65], v[194:197], v[166:169], v[50:65]
	ds_read_b128 v[122:125], v245 offset:20480
	v_exp_f32_e32 v130, v84
	v_exp_f32_e32 v131, v85
	s_add_i32 s23, s23, 3
	v_add_f32_e32 v132, v132, v130
	v_add_f32_e32 v133, v133, v131
	v_cvt_pk_bf16_f32 v163, v130, v131
	s_mov_b32 m0, s11
	s_cmp_gt_u32 s23, s16
	s_cbranch_scc1 .Lr1u1_LBB0_230
	global_load_lds_dwordx4 v214, s[50:51]
	s_add_i32 m0, s11, 0x2000
	s_nop 0
	global_load_lds_dwordx4 v214, s[4:5]
.Lr1u1_LBB0_230:
	v_mfma_f32_32x32x16_bf16 v[18:33], v[198:201], v[166:169], v[18:33]
	ds_read_b128 v[118:121], v245 offset:24576
	v_exp_f32_e32 v134, v86
	v_exp_f32_e32 v135, v87
	v_add_f32_e32 v132, v132, v134
	v_add_f32_e32 v133, v133, v135
	v_cvt_pk_bf16_f32 v164, v134, v135
	v_mfma_f32_32x32x16_bf16 v[2:17], v[202:205], v[166:169], v[2:17]
	ds_read_b128 v[114:117], v245 offset:28672
	v_exp_f32_e32 v134, v88
	v_exp_f32_e32 v135, v89
	v_add_f32_e32 v136, v132, v134
	v_add_f32_e32 v133, v133, v135
	v_cvt_pk_bf16_f32 v165, v134, v135
	s_waitcnt lgkmcnt(2)
	v_mfma_f32_32x32x16_bf16 v[34:49], v[126:129], v[174:177], v[34:49]
	ds_read_b128 v[126:129], v246 offset:16384
	v_exp_f32_e32 v134, v90
	v_exp_f32_e32 v135, v91
	v_add_f32_e32 v136, v136, v134
	v_add_f32_e32 v137, v133, v135
	v_cvt_pk_bf16_f32 v170, v134, v135
	v_mfma_f32_32x32x16_bf16 v[50:65], v[122:125], v[174:177], v[50:65]
	ds_read_b128 v[122:125], v246 offset:20480
	v_exp_f32_e32 v135, v92
	v_exp_f32_e32 v138, v93
	v_add_f32_e32 v133, v136, v135
	v_add_f32_e32 v134, v137, v138
	v_cvt_pk_bf16_f32 v171, v135, v138

.Lr2u1_LBB0_185:
	ds_read_b128 v[126:129], v244 offset:32768
	ds_read_b128 v[194:197], v244 offset:36864
	ds_read_b128 v[198:201], v244 offset:40960
	ds_read_b128 v[202:205], v244 offset:45056
	s_waitcnt lgkmcnt(4)
	v_mfma_f32_32x32x16_bf16 v[82:97], v[98:101], v[146:149], v[66:81]
	ds_read_b128 v[122:125], v240 offset:40960
	v_mfma_f32_32x32x16_bf16 v[98:113], v[114:117], v[146:149], v[66:81]
	ds_read_b128 v[114:117], v241 offset:32768
	v_mfma_f32_32x32x16_bf16 v[82:97], v[118:121], v[150:153], v[82:97]
	ds_read_b128 v[118:121], v241 offset:40960
	s_waitcnt lgkmcnt(0)
	v_mfma_f32_32x32x16_bf16 v[98:113], v[122:125], v[150:153], v[98:113]
	ds_read_b128 v[122:125], v243 offset:32768
	v_mfma_f32_32x32x16_bf16 v[82:97], v[114:117], v[154:157], v[82:97]
	ds_read_b128 v[114:117], v243 offset:40960
	v_mfma_f32_32x32x16_bf16 v[98:113], v[118:121], v[154:157], v[98:113]
	s_waitcnt lgkmcnt(0)
	v_mfma_f32_32x32x16_bf16 v[82:97], v[122:125], v[158:161], v[82:97]
	v_mfma_f32_32x32x16_bf16 v[98:113], v[114:117], v[158:161], v[98:113]
	s_nop 0
	s_add_i32 s22, s21, 64
	s_cmp_le_u32 s22, s20
	s_cbranch_scc0 .Lr2u1_Lnear_u1e
.Lr2u1_LBB0_188:
	v_mfma_f32_32x32x16_bf16 v[34:49], v[126:129], v[162:165], v[34:49]
	ds_read_b128 v[126:129], v245 offset:32768
	s_nop 0
	v_exp_f32_e32 v130, v82
	v_exp_f32_e32 v131, v83
	v_add_f32_e32 v132, v1, v130
	v_add_f32_e32 v133, v1, v131
	v_cvt_pk_bf16_f32 v166, v130, v131
	v_mfma_f32_32x32x16_bf16 v[50:65], v[194:197], v[162:165], v[50:65]
	ds_read_b128 v[122:125], v245 offset:36864
	v_exp_f32_e32 v134, v84
	v_exp_f32_e32 v135, v85
	s_add_i32 s22, s23, 2
	v_add_f32_e32 v130, v132, v134
	v_add_f32_e32 v131, v133, v135
	v_cvt_pk_bf16_f32 v167, v134, v135
	s_add_i32 m0, s11, 0x4000
	s_cmp_ge_u32 s22, s17
	s_cbranch_scc1 .Lr2u1_LBB0_190
	global_load_lds_dwordx4 v214, s[80:81]
	s_add_i32 m0, s11, 0x6000
	s_nop 0
	global_load_lds_dwordx4 v214, s[62:63]
.Lr2u1_LBB0_190:
	v_mfma_f32_32x32x16_bf16 v[18:33], v[198:201], v[162:165], v[18:33]
	ds_read_b128 v[118:121], v245 offset:40960
	v_exp_f32_e32 v132, v86
	v_exp_f32_e32 v133, v87
	v_add_f32_e32 v130, v130, v132
	v_add_f32_e32 v131, v131, v133
	v_cvt_pk_bf16_f32 v168, v132, v133
	v_mfma_f32_32x32x16_bf16 v[2:17], v[202:205], v[162:165], v[2:17]
	ds_read_b128 v[114:117], v245 offset:45056
	v_exp_f32_e32 v132, v88
	v_exp_f32_e32 v133, v89
	v_add_f32_e32 v134, v130, v132
	v_add_f32_e32 v131, v131, v133
	v_cvt_pk_bf16_f32 v169, v132, v133
	s_waitcnt lgkmcnt(2)
	v_mfma_f32_32x32x16_bf16 v[34:49], v[126:129], v[170:173], v[34:49]
	ds_read_b128 v[126:129], v246 offset:32768
	v_exp_f32_e32 v132, v90
	v_exp_f32_e32 v133, v91
	v_add_f32_e32 v134, v134, v132
	v_add_f32_e32 v135, v131, v133
	v_cvt_pk_bf16_f32 v174, v132, v133
	v_mfma_f32_32x32x16_bf16 v[50:65], v[122:125], v[170:173], v[50:65]
	ds_read_b128 v[122:125], v246 offset:36864
	v_exp_f32_e32 v133, v92
	v_exp_f32_e32 v136, v93
	v_add_f32_e32 v131, v134, v133
	v_add_f32_e32 v132, v135, v136
	v_cvt_pk_bf16_f32 v175, v133, v136

.Lr2u1_LBB0_225:
	ds_read_b128 v[126:129], v244 offset:49152
	ds_read_b128 v[194:197], v244 offset:53248
	ds_read_b128 v[198:201], v244 offset:57344
	ds_read_b128 v[202:205], v244 offset:61440
	s_waitcnt lgkmcnt(4)
	v_mfma_f32_32x32x16_bf16 v[82:97], v[98:101], v[146:149], v[66:81]
	ds_read_b128 v[122:125], v240 offset:8192
	v_mfma_f32_32x32x16_bf16 v[98:113], v[114:117], v[146:149], v[66:81]
	ds_read_b128 v[114:117], v241
	v_mfma_f32_32x32x16_bf16 v[82:97], v[118:121], v[150:153], v[82:97]
	ds_read_b128 v[118:121], v241 offset:8192
	s_waitcnt lgkmcnt(0)
	v_mfma_f32_32x32x16_bf16 v[98:113], v[122:125], v[150:153], v[98:113]
	ds_read_b128 v[122:125], v243
	v_mfma_f32_32x32x16_bf16 v[82:97], v[114:117], v[154:157], v[82:97]
	ds_read_b128 v[114:117], v243 offset:8192
	v_mfma_f32_32x32x16_bf16 v[98:113], v[118:121], v[154:157], v[98:113]
	s_waitcnt lgkmcnt(0)
	v_mfma_f32_32x32x16_bf16 v[82:97], v[122:125], v[158:161], v[82:97]
	v_mfma_f32_32x32x16_bf16 v[98:113], v[114:117], v[158:161], v[98:113]
	s_nop 0
	s_add_i32 s26, s21, 0x80
	s_cmp_le_u32 s26, s20
	s_cbranch_scc0 .Lr2u1_Lnear_u1o
.Lr2u1_LBB0_228:
	v_mfma_f32_32x32x16_bf16 v[34:49], v[126:129], v[166:169], v[34:49]
	ds_read_b128 v[126:129], v245 offset:49152
	s_nop 0
	v_exp_f32_e32 v130, v82
	v_exp_f32_e32 v131, v83
	v_add_f32_e32 v132, v1, v130
	v_add_f32_e32 v133, v1, v131
	v_cvt_pk_bf16_f32 v162, v130, v131
	v_mfma_f32_32x32x16_bf16 v[50:65], v[194:197], v[166:169], v[50:65]
	ds_read_b128 v[122:125], v245 offset:53248
	v_exp_f32_e32 v130, v84
	v_exp_f32_e32 v131, v85
	s_add_i32 s23, s23, 3
	v_add_f32_e32 v132, v132, v130
	v_add_f32_e32 v133, v133, v131
	v_cvt_pk_bf16_f32 v163, v130, v131
	s_add_i32 m0, s11, 0x8000
	s_cmp_gt_u32 s23, s16
	s_cbranch_scc1 .Lr2u1_LBB0_230
	global_load_lds_dwordx4 v214, s[50:51]
	s_add_i32 m0, s11, 0xa000
	s_nop 0
	global_load_lds_dwordx4 v214, s[4:5]
.Lr2u1_LBB0_230:
	v_mfma_f32_32x32x16_bf16 v[18:33], v[198:201], v[166:169], v[18:33]
	ds_read_b128 v[118:121], v245 offset:57344
	v_exp_f32_e32 v134, v86
	v_exp_f32_e32 v135, v87
	v_add_f32_e32 v132, v132, v134
	v_add_f32_e32 v133, v133, v135
	v_cvt_pk_bf16_f32 v164, v134, v135
	v_mfma_f32_32x32x16_bf16 v[2:17], v[202:205], v[166:169], v[2:17]
	ds_read_b128 v[114:117], v245 offset:61440
	v_exp_f32_e32 v134, v88
	v_exp_f32_e32 v135, v89
	v_add_f32_e32 v136, v132, v134
	v_add_f32_e32 v133, v133, v135
	v_cvt_pk_bf16_f32 v165, v134, v135
	s_waitcnt lgkmcnt(2)
	v_mfma_f32_32x32x16_bf16 v[34:49], v[126:129], v[174:177], v[34:49]
	ds_read_b128 v[126:129], v246 offset:49152
	v_exp_f32_e32 v134, v90
	v_exp_f32_e32 v135, v91
	v_add_f32_e32 v136, v136, v134
	v_add_f32_e32 v137, v133, v135
	v_cvt_pk_bf16_f32 v170, v134, v135
	v_mfma_f32_32x32x16_bf16 v[50:65], v[122:125], v[174:177], v[50:65]
	ds_read_b128 v[122:125], v246 offset:53248
	v_exp_f32_e32 v135, v92
	v_exp_f32_e32 v138, v93
	v_add_f32_e32 v133, v136, v135
	v_add_f32_e32 v134, v137, v138
	v_cvt_pk_bf16_f32 v171, v135, v138

.LBB0_288:
	ds_read_b128 v[126:129], v245 offset:16384
	ds_read_b128 v[194:197], v245 offset:20480
	ds_read_b128 v[198:201], v245 offset:24576
	ds_read_b128 v[202:205], v245 offset:28672
	s_waitcnt lgkmcnt(4)
	v_mfma_f32_32x32x16_bf16 v[82:97], v[98:101], v[146:149], v[66:81]
	ds_read_b128 v[122:125], v240 offset:24576
	v_mfma_f32_32x32x16_bf16 v[98:113], v[114:117], v[146:149], v[66:81]
	ds_read_b128 v[114:117], v241 offset:16384
	v_mfma_f32_32x32x16_bf16 v[82:97], v[118:121], v[150:153], v[82:97]
	ds_read_b128 v[118:121], v241 offset:24576
	s_waitcnt lgkmcnt(0)
	v_mfma_f32_32x32x16_bf16 v[98:113], v[122:125], v[150:153], v[98:113]
	ds_read_b128 v[122:125], v242 offset:16384
	v_mfma_f32_32x32x16_bf16 v[82:97], v[114:117], v[154:157], v[82:97]
	ds_read_b128 v[114:117], v242 offset:24576
	v_mfma_f32_32x32x16_bf16 v[98:113], v[118:121], v[154:157], v[98:113]
	s_waitcnt lgkmcnt(0)
	v_mfma_f32_32x32x16_bf16 v[82:97], v[122:125], v[158:161], v[82:97]
	v_mfma_f32_32x32x16_bf16 v[98:113], v[114:117], v[158:161], v[98:113]
	s_nop 0
	s_cmp_le_u32 s20, s16
	s_cbranch_scc0 .Lnear_u2e
.LBB0_291:
	v_mfma_f32_32x32x16_bf16 v[50:65], v[126:129], v[162:165], v[50:65]
	ds_read_b128 v[126:129], v246 offset:16384
	s_nop 1
	v_exp_f32_e32 v130, v82
	v_exp_f32_e32 v131, v83
	v_add_f32_e32 v132, v1, v130
	v_add_f32_e32 v133, v1, v131
	v_cvt_pk_bf16_f32 v166, v130, v131
	v_mfma_f32_32x32x16_bf16 v[34:49], v[194:197], v[162:165], v[34:49]
	ds_read_b128 v[122:125], v246 offset:20480
	v_exp_f32_e32 v134, v84
	v_exp_f32_e32 v135, v85
	s_add_i32 s21, s22, 2
	v_add_f32_e32 v130, v132, v134
	v_add_f32_e32 v131, v133, v135
	v_cvt_pk_bf16_f32 v167, v134, v135
	s_mov_b32 m0, s10
	s_cmp_ge_u32 s21, s18
	s_cbranch_scc1 .LBB0_293
	global_load_lds_dwordx4 v214, s[80:81]
	s_add_i32 m0, s10, 0x2000
	s_nop 0
	global_load_lds_dwordx4 v214, s[62:63]
.LBB0_293:
	v_mfma_f32_32x32x16_bf16 v[18:33], v[198:201], v[162:165], v[18:33]
	ds_read_b128 v[118:121], v246 offset:24576
	v_exp_f32_e32 v132, v86
	v_exp_f32_e32 v133, v87
	v_add_f32_e32 v130, v130, v132
	v_add_f32_e32 v131, v131, v133
	v_cvt_pk_bf16_f32 v168, v132, v133
	v_mfma_f32_32x32x16_bf16 v[2:17], v[202:205], v[162:165], v[2:17]
	ds_read_b128 v[114:117], v246 offset:28672
	v_exp_f32_e32 v0, v88
	v_exp_f32_e32 v132, v89
	v_add_f32_e32 v130, v130, v0
	v_add_f32_e32 v131, v131, v132
	v_cvt_pk_bf16_f32 v169, v0, v132
	s_waitcnt lgkmcnt(2)
	v_mfma_f32_32x32x16_bf16 v[50:65], v[126:129], v[170:173], v[50:65]
	ds_read_b128 v[126:129], v247 offset:16384
	v_exp_f32_e32 v132, v90
	v_exp_f32_e32 v133, v91
	v_add_f32_e32 v130, v130, v132
	v_add_f32_e32 v131, v131, v133
	v_cvt_pk_bf16_f32 v174, v132, v133
	v_mfma_f32_32x32x16_bf16 v[34:49], v[122:125], v[170:173], v[34:49]
	ds_read_b128 v[122:125], v247 offset:20480
	v_exp_f32_e32 v132, v92
	v_exp_f32_e32 v133, v93
	v_add_f32_e32 v130, v130, v132
	v_add_f32_e32 v131, v131, v133
	v_cvt_pk_bf16_f32 v175, v132, v133

.LBB0_328:
	ds_read_b128 v[126:129], v245 offset:32768
	ds_read_b128 v[194:197], v245 offset:36864
	ds_read_b128 v[198:201], v245 offset:40960
	ds_read_b128 v[202:205], v245 offset:45056
	s_waitcnt lgkmcnt(4)
	v_mfma_f32_32x32x16_bf16 v[82:97], v[98:101], v[146:149], v[66:81]
	ds_read_b128 v[122:125], v240 offset:40960
	v_mfma_f32_32x32x16_bf16 v[98:113], v[114:117], v[146:149], v[66:81]
	ds_read_b128 v[114:117], v241 offset:32768
	v_mfma_f32_32x32x16_bf16 v[82:97], v[118:121], v[150:153], v[82:97]
	ds_read_b128 v[118:121], v241 offset:40960
	s_waitcnt lgkmcnt(0)
	v_mfma_f32_32x32x16_bf16 v[98:113], v[122:125], v[150:153], v[98:113]
	ds_read_b128 v[122:125], v242 offset:32768
	v_mfma_f32_32x32x16_bf16 v[82:97], v[114:117], v[154:157], v[82:97]
	ds_read_b128 v[114:117], v242 offset:40960
	v_mfma_f32_32x32x16_bf16 v[98:113], v[118:121], v[154:157], v[98:113]
	s_waitcnt lgkmcnt(0)
	v_mfma_f32_32x32x16_bf16 v[82:97], v[122:125], v[158:161], v[82:97]
	v_mfma_f32_32x32x16_bf16 v[98:113], v[114:117], v[158:161], v[98:113]
	s_nop 0
	s_add_i32 s26, s20, 64
	s_cmp_le_u32 s26, s16
	s_cbranch_scc0 .Lnear_u2o
.LBB0_331:
	v_mfma_f32_32x32x16_bf16 v[50:65], v[126:129], v[166:169], v[50:65]
	ds_read_b128 v[126:129], v246 offset:32768
	s_nop 0
	v_exp_f32_e32 v130, v82
	v_exp_f32_e32 v131, v83
	v_add_f32_e32 v132, v1, v130
	v_add_f32_e32 v133, v1, v131
	v_cvt_pk_bf16_f32 v162, v130, v131
	v_mfma_f32_32x32x16_bf16 v[34:49], v[194:197], v[166:169], v[34:49]
	ds_read_b128 v[122:125], v246 offset:36864
	v_exp_f32_e32 v130, v84
	v_exp_f32_e32 v131, v85
	s_add_i32 s22, s22, 3
	v_add_f32_e32 v132, v132, v130
	v_add_f32_e32 v133, v133, v131
	v_cvt_pk_bf16_f32 v163, v130, v131
	s_add_i32 m0, s10, 0x4000
	s_cmp_gt_u32 s22, s17
	s_cbranch_scc1 .LBB0_333
	global_load_lds_dwordx4 v214, s[50:51]
	s_add_i32 m0, s10, 0x6000
	s_nop 0
	global_load_lds_dwordx4 v214, s[4:5]
.LBB0_333:
	v_mfma_f32_32x32x16_bf16 v[18:33], v[198:201], v[166:169], v[18:33]
	ds_read_b128 v[118:121], v246 offset:40960
	v_exp_f32_e32 v134, v86
	v_exp_f32_e32 v135, v87
	v_add_f32_e32 v132, v132, v134
	v_add_f32_e32 v133, v133, v135
	v_cvt_pk_bf16_f32 v164, v134, v135
	v_mfma_f32_32x32x16_bf16 v[2:17], v[202:205], v[166:169], v[2:17]
	ds_read_b128 v[114:117], v246 offset:45056
	v_exp_f32_e32 v0, v88
	v_exp_f32_e32 v134, v89
	v_add_f32_e32 v132, v132, v0
	v_add_f32_e32 v133, v133, v134
	v_cvt_pk_bf16_f32 v165, v0, v134
	s_waitcnt lgkmcnt(2)
	v_mfma_f32_32x32x16_bf16 v[50:65], v[126:129], v[174:177], v[50:65]
	ds_read_b128 v[126:129], v247 offset:32768
	v_exp_f32_e32 v134, v90
	v_exp_f32_e32 v135, v91
	v_add_f32_e32 v132, v132, v134
	v_add_f32_e32 v133, v133, v135
	v_cvt_pk_bf16_f32 v170, v134, v135
	v_mfma_f32_32x32x16_bf16 v[34:49], v[122:125], v[174:177], v[34:49]
	ds_read_b128 v[122:125], v247 offset:36864
	v_exp_f32_e32 v134, v92
	v_exp_f32_e32 v135, v93
	v_add_f32_e32 v132, v132, v134
	v_add_f32_e32 v133, v133, v135
	v_cvt_pk_bf16_f32 v171, v134, v135

.Lr1u2_LBB0_288:
	ds_read_b128 v[126:129], v245 offset:49152
	ds_read_b128 v[194:197], v245 offset:53248
	ds_read_b128 v[198:201], v245 offset:57344
	ds_read_b128 v[202:205], v245 offset:61440
	s_waitcnt lgkmcnt(4)
	v_mfma_f32_32x32x16_bf16 v[82:97], v[98:101], v[146:149], v[66:81]
	ds_read_b128 v[122:125], v240 offset:8192
	v_mfma_f32_32x32x16_bf16 v[98:113], v[114:117], v[146:149], v[66:81]
	ds_read_b128 v[114:117], v241
	v_mfma_f32_32x32x16_bf16 v[82:97], v[118:121], v[150:153], v[82:97]
	ds_read_b128 v[118:121], v241 offset:8192
	s_waitcnt lgkmcnt(0)
	v_mfma_f32_32x32x16_bf16 v[98:113], v[122:125], v[150:153], v[98:113]
	ds_read_b128 v[122:125], v242
	v_mfma_f32_32x32x16_bf16 v[82:97], v[114:117], v[154:157], v[82:97]
	ds_read_b128 v[114:117], v242 offset:8192
	v_mfma_f32_32x32x16_bf16 v[98:113], v[118:121], v[154:157], v[98:113]
	s_waitcnt lgkmcnt(0)
	v_mfma_f32_32x32x16_bf16 v[82:97], v[122:125], v[158:161], v[82:97]
	v_mfma_f32_32x32x16_bf16 v[98:113], v[114:117], v[158:161], v[98:113]
	s_nop 0
	s_cmp_le_u32 s20, s16
	s_cbranch_scc0 .Lr1u2_Lnear_u2e
.Lr1u2_LBB0_291:
	v_mfma_f32_32x32x16_bf16 v[50:65], v[126:129], v[162:165], v[50:65]
	ds_read_b128 v[126:129], v246 offset:49152
	s_nop 1
	v_exp_f32_e32 v130, v82
	v_exp_f32_e32 v131, v83
	v_add_f32_e32 v132, v1, v130
	v_add_f32_e32 v133, v1, v131
	v_cvt_pk_bf16_f32 v166, v130, v131
	v_mfma_f32_32x32x16_bf16 v[34:49], v[194:197], v[162:165], v[34:49]
	ds_read_b128 v[122:125], v246 offset:53248
	v_exp_f32_e32 v134, v84
	v_exp_f32_e32 v135, v85
	s_add_i32 s21, s22, 2
	v_add_f32_e32 v130, v132, v134
	v_add_f32_e32 v131, v133, v135
	v_cvt_pk_bf16_f32 v167, v134, v135
	s_add_i32 m0, s10, 0x8000
	s_cmp_ge_u32 s21, s18
	s_cbranch_scc1 .Lr1u2_LBB0_293
	global_load_lds_dwordx4 v214, s[80:81]
	s_add_i32 m0, s10, 0xa000
	s_nop 0
	global_load_lds_dwordx4 v214, s[62:63]
.Lr1u2_LBB0_293:
	v_mfma_f32_32x32x16_bf16 v[18:33], v[198:201], v[162:165], v[18:33]
	ds_read_b128 v[118:121], v246 offset:57344
	v_exp_f32_e32 v132, v86
	v_exp_f32_e32 v133, v87
	v_add_f32_e32 v130, v130, v132
	v_add_f32_e32 v131, v131, v133
	v_cvt_pk_bf16_f32 v168, v132, v133
	v_mfma_f32_32x32x16_bf16 v[2:17], v[202:205], v[162:165], v[2:17]
	ds_read_b128 v[114:117], v246 offset:61440
	v_exp_f32_e32 v0, v88
	v_exp_f32_e32 v132, v89
	v_add_f32_e32 v130, v130, v0
	v_add_f32_e32 v131, v131, v132
	v_cvt_pk_bf16_f32 v169, v0, v132
	s_waitcnt lgkmcnt(2)
	v_mfma_f32_32x32x16_bf16 v[50:65], v[126:129], v[170:173], v[50:65]
	ds_read_b128 v[126:129], v247 offset:49152
	v_exp_f32_e32 v132, v90
	v_exp_f32_e32 v133, v91
	v_add_f32_e32 v130, v130, v132
	v_add_f32_e32 v131, v131, v133
	v_cvt_pk_bf16_f32 v174, v132, v133
	v_mfma_f32_32x32x16_bf16 v[34:49], v[122:125], v[170:173], v[34:49]
	ds_read_b128 v[122:125], v247 offset:53248
	v_exp_f32_e32 v132, v92
	v_exp_f32_e32 v133, v93
	v_add_f32_e32 v130, v130, v132
	v_add_f32_e32 v131, v131, v133
	v_cvt_pk_bf16_f32 v175, v132, v133

.Lr1u2_LBB0_328:
	ds_read_b128 v[126:129], v245 offset:16384
	ds_read_b128 v[194:197], v245 offset:20480
	ds_read_b128 v[198:201], v245 offset:24576
	ds_read_b128 v[202:205], v245 offset:28672
	s_waitcnt lgkmcnt(4)
	v_mfma_f32_32x32x16_bf16 v[82:97], v[98:101], v[146:149], v[66:81]
	ds_read_b128 v[122:125], v240 offset:24576
	v_mfma_f32_32x32x16_bf16 v[98:113], v[114:117], v[146:149], v[66:81]
	ds_read_b128 v[114:117], v241 offset:16384
	v_mfma_f32_32x32x16_bf16 v[82:97], v[118:121], v[150:153], v[82:97]
	ds_read_b128 v[118:121], v241 offset:24576
	s_waitcnt lgkmcnt(0)
	v_mfma_f32_32x32x16_bf16 v[98:113], v[122:125], v[150:153], v[98:113]
	ds_read_b128 v[122:125], v242 offset:16384
	v_mfma_f32_32x32x16_bf16 v[82:97], v[114:117], v[154:157], v[82:97]
	ds_read_b128 v[114:117], v242 offset:24576
	v_mfma_f32_32x32x16_bf16 v[98:113], v[118:121], v[154:157], v[98:113]
	s_waitcnt lgkmcnt(0)
	v_mfma_f32_32x32x16_bf16 v[82:97], v[122:125], v[158:161], v[82:97]
	v_mfma_f32_32x32x16_bf16 v[98:113], v[114:117], v[158:161], v[98:113]
	s_nop 0
	s_add_i32 s26, s20, 64
	s_cmp_le_u32 s26, s16
	s_cbranch_scc0 .Lr1u2_Lnear_u2o
.Lr1u2_LBB0_331:
	v_mfma_f32_32x32x16_bf16 v[50:65], v[126:129], v[166:169], v[50:65]
	ds_read_b128 v[126:129], v246 offset:16384
	s_nop 0
	v_exp_f32_e32 v130, v82
	v_exp_f32_e32 v131, v83
	v_add_f32_e32 v132, v1, v130
	v_add_f32_e32 v133, v1, v131
	v_cvt_pk_bf16_f32 v162, v130, v131
	v_mfma_f32_32x32x16_bf16 v[34:49], v[194:197], v[166:169], v[34:49]
	ds_read_b128 v[122:125], v246 offset:20480
	v_exp_f32_e32 v130, v84
	v_exp_f32_e32 v131, v85
	s_add_i32 s22, s22, 3
	v_add_f32_e32 v132, v132, v130
	v_add_f32_e32 v133, v133, v131
	v_cvt_pk_bf16_f32 v163, v130, v131
	s_mov_b32 m0, s10
	s_cmp_gt_u32 s22, s17
	s_cbranch_scc1 .Lr1u2_LBB0_333
	global_load_lds_dwordx4 v214, s[50:51]
	s_add_i32 m0, s10, 0x2000
	s_nop 0
	global_load_lds_dwordx4 v214, s[4:5]
.Lr1u2_LBB0_333:
	v_mfma_f32_32x32x16_bf16 v[18:33], v[198:201], v[166:169], v[18:33]
	ds_read_b128 v[118:121], v246 offset:24576
	v_exp_f32_e32 v134, v86
	v_exp_f32_e32 v135, v87
	v_add_f32_e32 v132, v132, v134
	v_add_f32_e32 v133, v133, v135
	v_cvt_pk_bf16_f32 v164, v134, v135
	v_mfma_f32_32x32x16_bf16 v[2:17], v[202:205], v[166:169], v[2:17]
	ds_read_b128 v[114:117], v246 offset:28672
	v_exp_f32_e32 v0, v88
	v_exp_f32_e32 v134, v89
	v_add_f32_e32 v132, v132, v0
	v_add_f32_e32 v133, v133, v134
	v_cvt_pk_bf16_f32 v165, v0, v134
	s_waitcnt lgkmcnt(2)
	v_mfma_f32_32x32x16_bf16 v[50:65], v[126:129], v[174:177], v[50:65]
	ds_read_b128 v[126:129], v247 offset:16384
	v_exp_f32_e32 v134, v90
	v_exp_f32_e32 v135, v91
	v_add_f32_e32 v132, v132, v134
	v_add_f32_e32 v133, v133, v135
	v_cvt_pk_bf16_f32 v170, v134, v135
	v_mfma_f32_32x32x16_bf16 v[34:49], v[122:125], v[174:177], v[34:49]
	ds_read_b128 v[122:125], v247 offset:20480
	v_exp_f32_e32 v134, v92
	v_exp_f32_e32 v135, v93
	v_add_f32_e32 v132, v132, v134
	v_add_f32_e32 v133, v133, v135
	v_cvt_pk_bf16_f32 v171, v134, v135

.Lr2u2_LBB0_288:
	ds_read_b128 v[126:129], v245 offset:32768
	ds_read_b128 v[194:197], v245 offset:36864
	ds_read_b128 v[198:201], v245 offset:40960
	ds_read_b128 v[202:205], v245 offset:45056
	s_waitcnt lgkmcnt(4)
	v_mfma_f32_32x32x16_bf16 v[82:97], v[98:101], v[146:149], v[66:81]
	ds_read_b128 v[122:125], v240 offset:40960
	v_mfma_f32_32x32x16_bf16 v[98:113], v[114:117], v[146:149], v[66:81]
	ds_read_b128 v[114:117], v241 offset:32768
	v_mfma_f32_32x32x16_bf16 v[82:97], v[118:121], v[150:153], v[82:97]
	ds_read_b128 v[118:121], v241 offset:40960
	s_waitcnt lgkmcnt(0)
	v_mfma_f32_32x32x16_bf16 v[98:113], v[122:125], v[150:153], v[98:113]
	ds_read_b128 v[122:125], v242 offset:32768
	v_mfma_f32_32x32x16_bf16 v[82:97], v[114:117], v[154:157], v[82:97]
	ds_read_b128 v[114:117], v242 offset:40960
	v_mfma_f32_32x32x16_bf16 v[98:113], v[118:121], v[154:157], v[98:113]
	s_waitcnt lgkmcnt(0)
	v_mfma_f32_32x32x16_bf16 v[82:97], v[122:125], v[158:161], v[82:97]
	v_mfma_f32_32x32x16_bf16 v[98:113], v[114:117], v[158:161], v[98:113]
	s_nop 0
	s_cmp_le_u32 s20, s16
	s_cbranch_scc0 .Lr2u2_Lnear_u2e
.Lr2u2_LBB0_291:
	v_mfma_f32_32x32x16_bf16 v[50:65], v[126:129], v[162:165], v[50:65]
	ds_read_b128 v[126:129], v246 offset:32768
	s_nop 1
	v_exp_f32_e32 v130, v82
	v_exp_f32_e32 v131, v83
	v_add_f32_e32 v132, v1, v130
	v_add_f32_e32 v133, v1, v131
	v_cvt_pk_bf16_f32 v166, v130, v131
	v_mfma_f32_32x32x16_bf16 v[34:49], v[194:197], v[162:165], v[34:49]
	ds_read_b128 v[122:125], v246 offset:36864
	v_exp_f32_e32 v134, v84
	v_exp_f32_e32 v135, v85
	s_add_i32 s21, s22, 2
	v_add_f32_e32 v130, v132, v134
	v_add_f32_e32 v131, v133, v135
	v_cvt_pk_bf16_f32 v167, v134, v135
	s_add_i32 m0, s10, 0x4000
	s_cmp_ge_u32 s21, s18
	s_cbranch_scc1 .Lr2u2_LBB0_293
	global_load_lds_dwordx4 v214, s[80:81]
	s_add_i32 m0, s10, 0x6000
	s_nop 0
	global_load_lds_dwordx4 v214, s[62:63]
.Lr2u2_LBB0_293:
	v_mfma_f32_32x32x16_bf16 v[18:33], v[198:201], v[162:165], v[18:33]
	ds_read_b128 v[118:121], v246 offset:40960
	v_exp_f32_e32 v132, v86
	v_exp_f32_e32 v133, v87
	v_add_f32_e32 v130, v130, v132
	v_add_f32_e32 v131, v131, v133
	v_cvt_pk_bf16_f32 v168, v132, v133
	v_mfma_f32_32x32x16_bf16 v[2:17], v[202:205], v[162:165], v[2:17]
	ds_read_b128 v[114:117], v246 offset:45056
	v_exp_f32_e32 v0, v88
	v_exp_f32_e32 v132, v89
	v_add_f32_e32 v130, v130, v0
	v_add_f32_e32 v131, v131, v132
	v_cvt_pk_bf16_f32 v169, v0, v132
	s_waitcnt lgkmcnt(2)
	v_mfma_f32_32x32x16_bf16 v[50:65], v[126:129], v[170:173], v[50:65]
	ds_read_b128 v[126:129], v247 offset:32768
	v_exp_f32_e32 v132, v90
	v_exp_f32_e32 v133, v91
	v_add_f32_e32 v130, v130, v132
	v_add_f32_e32 v131, v131, v133
	v_cvt_pk_bf16_f32 v174, v132, v133
	v_mfma_f32_32x32x16_bf16 v[34:49], v[122:125], v[170:173], v[34:49]
	ds_read_b128 v[122:125], v247 offset:36864
	v_exp_f32_e32 v132, v92
	v_exp_f32_e32 v133, v93
	v_add_f32_e32 v130, v130, v132
	v_add_f32_e32 v131, v131, v133
	v_cvt_pk_bf16_f32 v175, v132, v133

.Lr2u2_LBB0_328:
	ds_read_b128 v[126:129], v245 offset:49152
	ds_read_b128 v[194:197], v245 offset:53248
	ds_read_b128 v[198:201], v245 offset:57344
	ds_read_b128 v[202:205], v245 offset:61440
	s_waitcnt lgkmcnt(4)
	v_mfma_f32_32x32x16_bf16 v[82:97], v[98:101], v[146:149], v[66:81]
	ds_read_b128 v[122:125], v240 offset:8192
	v_mfma_f32_32x32x16_bf16 v[98:113], v[114:117], v[146:149], v[66:81]
	ds_read_b128 v[114:117], v241
	v_mfma_f32_32x32x16_bf16 v[82:97], v[118:121], v[150:153], v[82:97]
	ds_read_b128 v[118:121], v241 offset:8192
	s_waitcnt lgkmcnt(0)
	v_mfma_f32_32x32x16_bf16 v[98:113], v[122:125], v[150:153], v[98:113]
	ds_read_b128 v[122:125], v242
	v_mfma_f32_32x32x16_bf16 v[82:97], v[114:117], v[154:157], v[82:97]
	ds_read_b128 v[114:117], v242 offset:8192
	v_mfma_f32_32x32x16_bf16 v[98:113], v[118:121], v[154:157], v[98:113]
	s_waitcnt lgkmcnt(0)
	v_mfma_f32_32x32x16_bf16 v[82:97], v[122:125], v[158:161], v[82:97]
	v_mfma_f32_32x32x16_bf16 v[98:113], v[114:117], v[158:161], v[98:113]
	s_nop 0
	s_add_i32 s26, s20, 64
	s_cmp_le_u32 s26, s16
	s_cbranch_scc0 .Lr2u2_Lnear_u2o
.Lr2u2_LBB0_331:
	v_mfma_f32_32x32x16_bf16 v[50:65], v[126:129], v[166:169], v[50:65]
	ds_read_b128 v[126:129], v246 offset:49152
	s_nop 0
	v_exp_f32_e32 v130, v82
	v_exp_f32_e32 v131, v83
	v_add_f32_e32 v132, v1, v130
	v_add_f32_e32 v133, v1, v131
	v_cvt_pk_bf16_f32 v162, v130, v131
	v_mfma_f32_32x32x16_bf16 v[34:49], v[194:197], v[166:169], v[34:49]
	ds_read_b128 v[122:125], v246 offset:53248
	v_exp_f32_e32 v130, v84
	v_exp_f32_e32 v131, v85
	s_add_i32 s22, s22, 3
	v_add_f32_e32 v132, v132, v130
	v_add_f32_e32 v133, v133, v131
	v_cvt_pk_bf16_f32 v163, v130, v131
	s_add_i32 m0, s10, 0x8000
	s_cmp_gt_u32 s22, s17
	s_cbranch_scc1 .Lr2u2_LBB0_333
	global_load_lds_dwordx4 v214, s[50:51]
	s_add_i32 m0, s10, 0xa000
	s_nop 0
	global_load_lds_dwordx4 v214, s[4:5]
.Lr2u2_LBB0_333:
	v_mfma_f32_32x32x16_bf16 v[18:33], v[198:201], v[166:169], v[18:33]
	ds_read_b128 v[118:121], v246 offset:57344
	v_exp_f32_e32 v134, v86
	v_exp_f32_e32 v135, v87
	v_add_f32_e32 v132, v132, v134
	v_add_f32_e32 v133, v133, v135
	v_cvt_pk_bf16_f32 v164, v134, v135
	v_mfma_f32_32x32x16_bf16 v[2:17], v[202:205], v[166:169], v[2:17]
	ds_read_b128 v[114:117], v246 offset:61440
	v_exp_f32_e32 v0, v88
	v_exp_f32_e32 v134, v89
	v_add_f32_e32 v132, v132, v0
	v_add_f32_e32 v133, v133, v134
	v_cvt_pk_bf16_f32 v165, v0, v134
	s_waitcnt lgkmcnt(2)
	v_mfma_f32_32x32x16_bf16 v[50:65], v[126:129], v[174:177], v[50:65]
	ds_read_b128 v[126:129], v247 offset:49152
	v_exp_f32_e32 v134, v90
	v_exp_f32_e32 v135, v91
	v_add_f32_e32 v132, v132, v134
	v_add_f32_e32 v133, v133, v135
	v_cvt_pk_bf16_f32 v170, v134, v135
	v_mfma_f32_32x32x16_bf16 v[34:49], v[122:125], v[174:177], v[34:49]
	ds_read_b128 v[122:125], v247 offset:53248
	v_exp_f32_e32 v134, v92
	v_exp_f32_e32 v135, v93
	v_add_f32_e32 v132, v132, v134
	v_add_f32_e32 v133, v133, v135
	v_cvt_pk_bf16_f32 v171, v134, v135
